# v18 + LayerNorm sample rows: split-K slab loads issued per column group with two groups in flight instead of ~10 dependent batches (same addition order)
# speedup vs baseline: 1.0069x; 1.0069x over previous
;     ...
;     if (mode != 0 && r >= T_P) {
; #pragma unroll
;       for (int i = 0; i < 4; i++) v[i] = make_float4(0.f, 0.f, 0.f, 0.f);
;       for (int qk0 = 0; qk0 < kparts; qk0 += 4) {
;         float4 t4[4][4];
; #pragma unroll
;         for (int u = 0; u < 4; u++) {
;           const float4* sl = (const float4*)((const float*)(p.ws + WS_SLAB) + ((size_t)(qk0 + u) * 512 + (r - T_P)) * 1024);
; #pragma unroll
;           for (int i = 0; i < 4; i++) t4[u][i] = (qk0 + u < kparts) ? sl[lane + 64 * i] : make_float4(0.f, 0.f, 0.f, 0.f);
;         }
; #pragma unroll
;         for (int u = 0; u < 4; u++)
; #pragma unroll
;           for (int i = 0; i < 4; i++) { v[i].x += t4[u][i].x; v[i].y += t4[u][i].y; v[i].z += t4[u][i].z; v[i].w += t4[u][i].w; }
;       }
;     }
.LBB0_19:
	s_or_b64 exec, exec, s[6:7]
	s_movk_i32 s2, 0x3fff
	v_cmp_lt_i32_e32 vcc, s2, v84
	s_and_saveexec_b64 s[6:7], vcc
	s_cbranch_execz .LBB0_21
	v_add_u32_e32 v0, 0xffffc000, v84
	v_readlane_b32 s2, v251, 9
	v_readlane_b32 s3, v251, 10
	s_waitcnt vmcnt(0)
	v_lshlrev_b64 v[84:85], 12, v[0:1]
	v_mov_b32_e32 v77, v1
	v_lshl_add_u64 v[84:85], s[2:3], 0, v[84:85]
	v_lshl_add_u64 v[104:105], v[84:85], 0, v[76:77]
	s_mov_b64 s[2:3], 0x200000
	v_lshl_add_u64 v[106:107], v[104:105], 0, s[2:3]
	v_lshl_add_u64 v[116:117], v[106:107], 0, s[2:3]
	v_lshl_add_u64 v[118:119], v[116:117], 0, s[2:3]
	v_lshl_add_u64 v[120:121], v[118:119], 0, s[2:3]
	v_lshl_add_u64 v[122:123], v[120:121], 0, s[2:3]
	v_lshl_add_u64 v[124:125], v[122:123], 0, s[2:3]
	v_lshl_add_u64 v[126:127], v[124:125], 0, s[2:3]
	v_lshl_add_u64 v[132:133], v[126:127], 0, s[2:3]
	v_lshl_add_u64 v[134:135], v[132:133], 0, s[2:3]
	v_lshl_add_u64 v[136:137], v[134:135], 0, s[2:3]
	global_load_dwordx4 v[176:179], v[104:105], off
	global_load_dwordx4 v[180:183], v[106:107], off
	global_load_dwordx4 v[184:187], v[116:117], off
	global_load_dwordx4 v[188:191], v[118:119], off
	global_load_dwordx4 v[192:195], v[120:121], off
	global_load_dwordx4 v[196:199], v[122:123], off
	global_load_dwordx4 v[200:203], v[124:125], off
	global_load_dwordx4 v[204:207], v[126:127], off
	global_load_dwordx4 v[208:211], v[132:133], off
	global_load_dwordx4 v[212:215], v[134:135], off
	global_load_dwordx4 v[216:219], v[136:137], off
	global_load_dwordx4 v[220:223], v[104:105], off offset:1024
	global_load_dwordx4 v[224:227], v[106:107], off offset:1024
	global_load_dwordx4 v[228:231], v[116:117], off offset:1024
	global_load_dwordx4 v[232:235], v[118:119], off offset:1024
	global_load_dwordx4 v[236:239], v[120:121], off offset:1024
	global_load_dwordx4 v[240:243], v[122:123], off offset:1024
	global_load_dwordx4 v[244:247], v[124:125], off offset:1024
	global_load_dwordx4 v[88:91], v[126:127], off offset:1024
	global_load_dwordx4 v[92:95], v[132:133], off offset:1024
	global_load_dwordx4 v[96:99], v[134:135], off offset:1024
	global_load_dwordx4 v[100:103], v[136:137], off offset:1024
	s_waitcnt vmcnt(11)
	v_pk_add_f32 v[62:63], v[176:177], 0 op_sel_hi:[1,0]
	v_pk_add_f32 v[64:65], v[178:179], 0 op_sel_hi:[1,0]
	v_pk_add_f32 v[62:63], v[62:63], v[180:181]
	v_pk_add_f32 v[64:65], v[64:65], v[182:183]
	v_pk_add_f32 v[62:63], v[62:63], v[184:185]
	v_pk_add_f32 v[64:65], v[64:65], v[186:187]
	v_pk_add_f32 v[62:63], v[62:63], v[188:189]
	v_pk_add_f32 v[64:65], v[64:65], v[190:191]
	v_pk_add_f32 v[62:63], v[62:63], v[192:193]
	v_pk_add_f32 v[64:65], v[64:65], v[194:195]
	v_pk_add_f32 v[62:63], v[62:63], v[196:197]
	v_pk_add_f32 v[64:65], v[64:65], v[198:199]
	v_pk_add_f32 v[62:63], v[62:63], v[200:201]
	v_pk_add_f32 v[64:65], v[64:65], v[202:203]
	v_pk_add_f32 v[62:63], v[62:63], v[204:205]
	v_pk_add_f32 v[64:65], v[64:65], v[206:207]
	v_pk_add_f32 v[62:63], v[62:63], v[208:209]
	v_pk_add_f32 v[64:65], v[64:65], v[210:211]
	v_pk_add_f32 v[62:63], v[62:63], v[212:213]
	v_pk_add_f32 v[64:65], v[64:65], v[214:215]
	v_pk_add_f32 v[62:63], v[62:63], v[216:217]
	v_pk_add_f32 v[64:65], v[64:65], v[218:219]
	v_pk_add_f32 v[62:63], v[62:63], 0 op_sel_hi:[1,0]
	v_pk_add_f32 v[64:65], v[64:65], 0 op_sel_hi:[1,0]
	global_load_dwordx4 v[176:179], v[104:105], off offset:2048
	global_load_dwordx4 v[180:183], v[106:107], off offset:2048
	global_load_dwordx4 v[184:187], v[116:117], off offset:2048
	global_load_dwordx4 v[188:191], v[118:119], off offset:2048
	global_load_dwordx4 v[192:195], v[120:121], off offset:2048
	global_load_dwordx4 v[196:199], v[122:123], off offset:2048
	global_load_dwordx4 v[200:203], v[124:125], off offset:2048
	global_load_dwordx4 v[204:207], v[126:127], off offset:2048
	global_load_dwordx4 v[208:211], v[132:133], off offset:2048
	global_load_dwordx4 v[212:215], v[134:135], off offset:2048
	global_load_dwordx4 v[216:219], v[136:137], off offset:2048
	s_waitcnt vmcnt(11)
;     ...
;       for (int qk0 = 0; qk0 < kparts; qk0 += 4) {
;         float4 t4[4][4];
; #pragma unroll
;         for (int u = 0; u < 4; u++) {
;           const float4* sl = (const float4*)((const float*)(p.ws + WS_SLAB) + ((size_t)(qk0 + u) * 512 + (r - T_P)) * 1024);
; #pragma unroll
;           for (int i = 0; i < 4; i++) t4[u][i] = (qk0 + u < kparts) ? sl[lane + 64 * i] : make_float4(0.f, 0.f, 0.f, 0.f);
;         }
; #pragma unroll
;         for (int u = 0; u < 4; u++)
; #pragma unroll
;           for (int i = 0; i < 4; i++) { v[i].x += t4[u][i].x; v[i].y += t4[u][i].y; v[i].z += t4[u][i].z; v[i].w += t4[u][i].w; }
;       }
	v_pk_add_f32 v[58:59], v[220:221], 0 op_sel_hi:[1,0]
	v_pk_add_f32 v[60:61], v[222:223], 0 op_sel_hi:[1,0]
	v_pk_add_f32 v[58:59], v[58:59], v[224:225]
	v_pk_add_f32 v[60:61], v[60:61], v[226:227]
	v_pk_add_f32 v[58:59], v[58:59], v[228:229]
	v_pk_add_f32 v[60:61], v[60:61], v[230:231]
	v_pk_add_f32 v[58:59], v[58:59], v[232:233]
	v_pk_add_f32 v[60:61], v[60:61], v[234:235]
	v_pk_add_f32 v[58:59], v[58:59], v[236:237]
	v_pk_add_f32 v[60:61], v[60:61], v[238:239]
	v_pk_add_f32 v[58:59], v[58:59], v[240:241]
	v_pk_add_f32 v[60:61], v[60:61], v[242:243]
	v_pk_add_f32 v[58:59], v[58:59], v[244:245]
	v_pk_add_f32 v[60:61], v[60:61], v[246:247]
	v_pk_add_f32 v[58:59], v[58:59], v[88:89]
	v_pk_add_f32 v[60:61], v[60:61], v[90:91]
	v_pk_add_f32 v[58:59], v[58:59], v[92:93]
	v_pk_add_f32 v[60:61], v[60:61], v[94:95]
	v_pk_add_f32 v[58:59], v[58:59], v[96:97]
	v_pk_add_f32 v[60:61], v[60:61], v[98:99]
	v_pk_add_f32 v[58:59], v[58:59], v[100:101]
	v_pk_add_f32 v[60:61], v[60:61], v[102:103]
	v_pk_add_f32 v[58:59], v[58:59], 0 op_sel_hi:[1,0]
	v_pk_add_f32 v[60:61], v[60:61], 0 op_sel_hi:[1,0]
	global_load_dwordx4 v[220:223], v[104:105], off offset:3072
	global_load_dwordx4 v[224:227], v[106:107], off offset:3072
	global_load_dwordx4 v[228:231], v[116:117], off offset:3072
	global_load_dwordx4 v[232:235], v[118:119], off offset:3072
	global_load_dwordx4 v[236:239], v[120:121], off offset:3072
	global_load_dwordx4 v[240:243], v[122:123], off offset:3072
	global_load_dwordx4 v[244:247], v[124:125], off offset:3072
	global_load_dwordx4 v[88:91], v[126:127], off offset:3072
	global_load_dwordx4 v[92:95], v[132:133], off offset:3072
	global_load_dwordx4 v[96:99], v[134:135], off offset:3072
	global_load_dwordx4 v[100:103], v[136:137], off offset:3072
	s_waitcnt vmcnt(11)
	v_pk_add_f32 v[54:55], v[176:177], 0 op_sel_hi:[1,0]
	v_pk_add_f32 v[56:57], v[178:179], 0 op_sel_hi:[1,0]
	v_pk_add_f32 v[54:55], v[54:55], v[180:181]
	v_pk_add_f32 v[56:57], v[56:57], v[182:183]
	v_pk_add_f32 v[54:55], v[54:55], v[184:185]
	v_pk_add_f32 v[56:57], v[56:57], v[186:187]
	v_pk_add_f32 v[54:55], v[54:55], v[188:189]
	v_pk_add_f32 v[56:57], v[56:57], v[190:191]
	v_pk_add_f32 v[54:55], v[54:55], v[192:193]
	v_pk_add_f32 v[56:57], v[56:57], v[194:195]
	v_pk_add_f32 v[54:55], v[54:55], v[196:197]
	v_pk_add_f32 v[56:57], v[56:57], v[198:199]
	v_pk_add_f32 v[54:55], v[54:55], v[200:201]
	v_pk_add_f32 v[56:57], v[56:57], v[202:203]
	v_pk_add_f32 v[54:55], v[54:55], v[204:205]
	v_pk_add_f32 v[56:57], v[56:57], v[206:207]
	v_pk_add_f32 v[54:55], v[54:55], v[208:209]
	v_pk_add_f32 v[56:57], v[56:57], v[210:211]
	v_pk_add_f32 v[54:55], v[54:55], v[212:213]
	v_pk_add_f32 v[56:57], v[56:57], v[214:215]
	v_pk_add_f32 v[54:55], v[54:55], v[216:217]
	v_pk_add_f32 v[56:57], v[56:57], v[218:219]
	v_pk_add_f32 v[54:55], v[54:55], 0 op_sel_hi:[1,0]
	v_pk_add_f32 v[56:57], v[56:57], 0 op_sel_hi:[1,0]
	s_waitcnt vmcnt(0)
	v_pk_add_f32 v[50:51], v[220:221], 0 op_sel_hi:[1,0]
	v_pk_add_f32 v[52:53], v[222:223], 0 op_sel_hi:[1,0]
	v_pk_add_f32 v[50:51], v[50:51], v[224:225]
	v_pk_add_f32 v[52:53], v[52:53], v[226:227]
	v_pk_add_f32 v[50:51], v[50:51], v[228:229]
	v_pk_add_f32 v[52:53], v[52:53], v[230:231]
	v_pk_add_f32 v[50:51], v[50:51], v[232:233]
	v_pk_add_f32 v[52:53], v[52:53], v[234:235]
	v_pk_add_f32 v[50:51], v[50:51], v[236:237]
	v_pk_add_f32 v[52:53], v[52:53], v[238:239]
	v_pk_add_f32 v[50:51], v[50:51], v[240:241]
	v_pk_add_f32 v[52:53], v[52:53], v[242:243]
	v_pk_add_f32 v[50:51], v[50:51], v[244:245]
	v_pk_add_f32 v[52:53], v[52:53], v[246:247]
	v_pk_add_f32 v[50:51], v[50:51], v[88:89]
	v_pk_add_f32 v[52:53], v[52:53], v[90:91]
	v_pk_add_f32 v[50:51], v[50:51], v[92:93]
	v_pk_add_f32 v[52:53], v[52:53], v[94:95]
	v_pk_add_f32 v[50:51], v[50:51], v[96:97]
	v_pk_add_f32 v[52:53], v[52:53], v[98:99]
	v_pk_add_f32 v[50:51], v[50:51], v[100:101]
	v_pk_add_f32 v[52:53], v[52:53], v[102:103]
	v_pk_add_f32 v[50:51], v[50:51], 0 op_sel_hi:[1,0]
	v_pk_add_f32 v[52:53], v[52:53], 0 op_sel_hi:[1,0]

;     ...
;     if (mode != 0 && r >= T_P) {
; #pragma unroll
;       for (int i = 0; i < 4; i++) v[i] = make_float4(0.f, 0.f, 0.f, 0.f);
;       for (int qk0 = 0; qk0 < kparts; qk0 += 4) {
;         float4 t4[4][4];
; #pragma unroll
;         for (int u = 0; u < 4; u++) {
;           const float4* sl = (const float4*)((const float*)(p.ws + WS_SLAB) + ((size_t)(qk0 + u) * 512 + (r - T_P)) * 1024);
; #pragma unroll
;           for (int i = 0; i < 4; i++) t4[u][i] = (qk0 + u < kparts) ? sl[lane + 64 * i] : make_float4(0.f, 0.f, 0.f, 0.f);
;         }
; #pragma unroll
;         for (int u = 0; u < 4; u++)
; #pragma unroll
;           for (int i = 0; i < 4; i++) { v[i].x += t4[u][i].x; v[i].y += t4[u][i].y; v[i].z += t4[u][i].z; v[i].w += t4[u][i].w; }
;       }
;     }
.LBB0_750:
	s_or_b64 exec, exec, s[10:11]
	s_movk_i32 s0, 0x3fff
	v_cmp_lt_i32_e64 s[4:5], s0, v78
	s_and_saveexec_b64 s[10:11], s[4:5]
	s_cbranch_execz .LBB0_747
	v_add_u32_e32 v0, 0xffffc000, v78
	v_readlane_b32 s2, v251, 9
	v_readlane_b32 s3, v251, 10
	s_waitcnt vmcnt(0)
	v_lshlrev_b64 v[80:81], 12, v[0:1]
	v_mov_b32_e32 v71, v1
	v_lshl_add_u64 v[80:81], s[2:3], 0, v[80:81]
	v_lshl_add_u64 v[84:85], v[80:81], 0, v[70:71]
	s_mov_b64 s[2:3], 0x200000
	v_lshl_add_u64 v[86:87], v[84:85], 0, s[2:3]
	v_lshl_add_u64 v[88:89], v[86:87], 0, s[2:3]
	v_lshl_add_u64 v[90:91], v[88:89], 0, s[2:3]
	v_lshl_add_u64 v[92:93], v[90:91], 0, s[2:3]
	v_lshl_add_u64 v[94:95], v[92:93], 0, s[2:3]
	v_lshl_add_u64 v[96:97], v[94:95], 0, s[2:3]
	v_lshl_add_u64 v[98:99], v[96:97], 0, s[2:3]
	global_load_dwordx4 v[176:179], v[84:85], off
	global_load_dwordx4 v[180:183], v[86:87], off
	global_load_dwordx4 v[184:187], v[88:89], off
	global_load_dwordx4 v[188:191], v[90:91], off
	global_load_dwordx4 v[192:195], v[92:93], off
	global_load_dwordx4 v[196:199], v[94:95], off
	global_load_dwordx4 v[200:203], v[96:97], off
	global_load_dwordx4 v[204:207], v[98:99], off
	global_load_dwordx4 v[208:211], v[84:85], off offset:1024
	global_load_dwordx4 v[212:215], v[86:87], off offset:1024
	global_load_dwordx4 v[216:219], v[88:89], off offset:1024
	global_load_dwordx4 v[220:223], v[90:91], off offset:1024
	global_load_dwordx4 v[224:227], v[92:93], off offset:1024
	global_load_dwordx4 v[228:231], v[94:95], off offset:1024
	global_load_dwordx4 v[232:235], v[96:97], off offset:1024
	global_load_dwordx4 v[236:239], v[98:99], off offset:1024
	s_waitcnt vmcnt(8)
	v_pk_add_f32 v[58:59], v[176:177], 0 op_sel_hi:[1,0]
	v_pk_add_f32 v[60:61], v[178:179], 0 op_sel_hi:[1,0]
	v_pk_add_f32 v[58:59], v[58:59], v[180:181]
	v_pk_add_f32 v[60:61], v[60:61], v[182:183]
	v_pk_add_f32 v[58:59], v[58:59], v[184:185]
	v_pk_add_f32 v[60:61], v[60:61], v[186:187]
	v_pk_add_f32 v[58:59], v[58:59], v[188:189]
	v_pk_add_f32 v[60:61], v[60:61], v[190:191]
	v_pk_add_f32 v[58:59], v[58:59], v[192:193]
	v_pk_add_f32 v[60:61], v[60:61], v[194:195]
	v_pk_add_f32 v[58:59], v[58:59], v[196:197]
	v_pk_add_f32 v[60:61], v[60:61], v[198:199]
	v_pk_add_f32 v[58:59], v[58:59], v[200:201]
	v_pk_add_f32 v[60:61], v[60:61], v[202:203]
	v_pk_add_f32 v[58:59], v[58:59], v[204:205]
	v_pk_add_f32 v[60:61], v[60:61], v[206:207]
	global_load_dwordx4 v[176:179], v[84:85], off offset:2048
	global_load_dwordx4 v[180:183], v[86:87], off offset:2048
	global_load_dwordx4 v[184:187], v[88:89], off offset:2048
	global_load_dwordx4 v[188:191], v[90:91], off offset:2048
	global_load_dwordx4 v[192:195], v[92:93], off offset:2048
	global_load_dwordx4 v[196:199], v[94:95], off offset:2048
	global_load_dwordx4 v[200:203], v[96:97], off offset:2048
	global_load_dwordx4 v[204:207], v[98:99], off offset:2048
	s_waitcnt vmcnt(8)
	v_pk_add_f32 v[50:51], v[208:209], 0 op_sel_hi:[1,0]
	v_pk_add_f32 v[52:53], v[210:211], 0 op_sel_hi:[1,0]
	v_pk_add_f32 v[50:51], v[50:51], v[212:213]
	v_pk_add_f32 v[52:53], v[52:53], v[214:215]
	v_pk_add_f32 v[50:51], v[50:51], v[216:217]
	v_pk_add_f32 v[52:53], v[52:53], v[218:219]
	v_pk_add_f32 v[50:51], v[50:51], v[220:221]
	v_pk_add_f32 v[52:53], v[52:53], v[222:223]
	v_pk_add_f32 v[50:51], v[50:51], v[224:225]
	v_pk_add_f32 v[52:53], v[52:53], v[226:227]
	v_pk_add_f32 v[50:51], v[50:51], v[228:229]
	v_pk_add_f32 v[52:53], v[52:53], v[230:231]
	v_pk_add_f32 v[50:51], v[50:51], v[232:233]
	v_pk_add_f32 v[52:53], v[52:53], v[234:235]
	v_pk_add_f32 v[50:51], v[50:51], v[236:237]
	v_pk_add_f32 v[52:53], v[52:53], v[238:239]
	global_load_dwordx4 v[208:211], v[84:85], off offset:3072
	global_load_dwordx4 v[212:215], v[86:87], off offset:3072
	global_load_dwordx4 v[216:219], v[88:89], off offset:3072
	global_load_dwordx4 v[220:223], v[90:91], off offset:3072
	global_load_dwordx4 v[224:227], v[92:93], off offset:3072
	global_load_dwordx4 v[228:231], v[94:95], off offset:3072
	global_load_dwordx4 v[232:235], v[96:97], off offset:3072
	global_load_dwordx4 v[236:239], v[98:99], off offset:3072
	s_waitcnt vmcnt(8)
	v_pk_add_f32 v[54:55], v[176:177], 0 op_sel_hi:[1,0]
	v_pk_add_f32 v[56:57], v[178:179], 0 op_sel_hi:[1,0]
	v_pk_add_f32 v[54:55], v[54:55], v[180:181]
	v_pk_add_f32 v[56:57], v[56:57], v[182:183]
	v_pk_add_f32 v[54:55], v[54:55], v[184:185]
	v_pk_add_f32 v[56:57], v[56:57], v[186:187]
	v_pk_add_f32 v[54:55], v[54:55], v[188:189]
	v_pk_add_f32 v[56:57], v[56:57], v[190:191]
	v_pk_add_f32 v[54:55], v[54:55], v[192:193]
	v_pk_add_f32 v[56:57], v[56:57], v[194:195]
	v_pk_add_f32 v[54:55], v[54:55], v[196:197]
	v_pk_add_f32 v[56:57], v[56:57], v[198:199]
	v_pk_add_f32 v[54:55], v[54:55], v[200:201]
	v_pk_add_f32 v[56:57], v[56:57], v[202:203]
	v_pk_add_f32 v[54:55], v[54:55], v[204:205]
	v_pk_add_f32 v[56:57], v[56:57], v[206:207]
	s_waitcnt vmcnt(0)
	v_pk_add_f32 v[62:63], v[208:209], 0 op_sel_hi:[1,0]
	v_pk_add_f32 v[64:65], v[210:211], 0 op_sel_hi:[1,0]
	v_pk_add_f32 v[62:63], v[62:63], v[212:213]
	v_pk_add_f32 v[64:65], v[64:65], v[214:215]
	v_pk_add_f32 v[62:63], v[62:63], v[216:217]
	v_pk_add_f32 v[64:65], v[64:65], v[218:219]
	v_pk_add_f32 v[62:63], v[62:63], v[220:221]
	v_pk_add_f32 v[64:65], v[64:65], v[222:223]
	v_pk_add_f32 v[62:63], v[62:63], v[224:225]
	v_pk_add_f32 v[64:65], v[64:65], v[226:227]
	v_pk_add_f32 v[62:63], v[62:63], v[228:229]
	v_pk_add_f32 v[64:65], v[64:65], v[230:231]
	v_pk_add_f32 v[62:63], v[62:63], v[232:233]
	v_pk_add_f32 v[64:65], v[64:65], v[234:235]
	v_pk_add_f32 v[62:63], v[62:63], v[236:237]
	v_pk_add_f32 v[64:65], v[64:65], v[238:239]
	s_branch .LBB0_747
